# ssm_gen (P1 instance) KC f32-MFMA loop: two (dir,lag) blocks per wave run as two interleaved accumulation chains
# baseline (speedup 1.0000x reference)
; __device__ __forceinline__ void ssm_gen(LAS unsigned char* lds, const Args& a, int layer, int g, int j8) {
;     ...
;         const int wv = tid >> 6, l = tid & 63, col = l & 15, kq = l >> 4, part = kq & 1;
; #pragma unroll 1
;         for (int blk = wv; blk < 36; blk += 8) {
;             const int dir = blk < ndf ? 0 : 1, d = dir ? blk - ndf : blk;
;             f32x4 acc = {0.f, 0.f, 0.f, 0.f};
; #pragma unroll 8
;             for (int st = 0; st < 32; ++st) {
;                 const int p = 2 * st + (kq >> 1);
;                 const f32x2 c = CT[(dir * 64 + p) * 16 + col], w = PW[(dir * 33 + d) * 64 + p], bb = BB[(dir * 64 + p) * 16 + col];
;                 const float av = part ? -(c.x * w.y + c.y * w.x) : (c.x * w.x - c.y * w.y);
;                 const float bv = part ? bb.y : bb.x;
;                 acc = __builtin_amdgcn_mfma_f32_16x16x4f32(av, bv, acc, 0, 0, 0);
.LBB0_366:
	s_or_b64 exec, exec, s[10:11]
	v_ashrrev_i32_e32 v13, 6, v12
	v_cmp_gt_i32_e32 vcc, 36, v13
	s_and_saveexec_b64 s[10:11], vcc
	s_cbranch_execz .LBB0_371
	v_and_b32_e32 v0, 16, v12
	v_cmp_eq_u32_e32 vcc, 0, v0
	v_lshlrev_b32_e32 v0, 4, v10
	v_and_b32_e32 v0, 0x300, v0
	v_readlane_b32 s1, v254, 49
	v_lshrrev_b32_e32 v16, 5, v10
	v_lshl_add_u32 v18, v16, 3, 0
	v_add3_u32 v14, s1, v0, v14
	v_readlane_b32 s1, v254, 50
	s_mov_b64 s[16:17], 0
	s_nop 0
	v_lshl_add_u32 v17, v11, 3, s1
	s_mov_b32 s7, 0
.Lkc_pair:
	v_mov_b32_e32 v0, s82
	v_cmp_gt_i32_e64 s[38:39], s82, v13
	s_mov_b32 s5, 0
	s_nop 0
	v_cndmask_b32_e64 v19, v0, 0, s[38:39]
	v_cndmask_b32_e64 v0, 64, 0, s[38:39]
	v_cndmask_b32_e64 v1, 33, 0, s[38:39]
	v_or_b32_e32 v0, v16, v0
	v_lshl_add_u32 v20, v0, 7, v17
	v_add_u32_e32 v0, v1, v13
	v_sub_u32_e32 v0, v0, v19
	v_lshl_add_u32 v21, v0, 9, v18
	v_mov_b32_e32 v0, 0
	v_mov_b32_e32 v1, v0
	v_mov_b32_e32 v2, v0
	v_mov_b32_e32 v3, v0
	v_add_u32_e32 v144, 8, v13
	v_mov_b32_e32 v110, s82
	v_cmp_gt_i32_e64 s[38:39], s82, v144
	s_mov_b32 s5, 0
	s_nop 0
	v_cndmask_b32_e64 v129, v110, 0, s[38:39]
	v_cndmask_b32_e64 v110, 64, 0, s[38:39]
	v_cndmask_b32_e64 v111, 33, 0, s[38:39]
	v_or_b32_e32 v110, v16, v110
	v_lshl_add_u32 v130, v110, 7, v17
	v_add_u32_e32 v110, v111, v144
	v_sub_u32_e32 v110, v110, v129
	v_lshl_add_u32 v131, v110, 9, v18
	v_mov_b32_e32 v110, 0
	v_mov_b32_e32 v111, v110
	v_mov_b32_e32 v112, v110
	v_mov_b32_e32 v113, v110
	s_mov_b32 s5, 0
.Lkc_trip:
	v_add_u32_e32 v32, 0x4000, v20
	v_add_u32_e32 v142, 0x4000, v130
	ds_read2_b64 v[4:7], v32 offset1:32
	ds_read2_b64 v[114:117], v142 offset1:32
	v_add_u32_e32 v33, s5, v21
	v_add_u32_e32 v143, s5, v131
	ds_read2_b64 v[8:11], v20 offset1:32
	ds_read2_b64 v[118:121], v130 offset1:32
	ds_read2_b64 v[22:25], v33 offset1:2
	ds_read2_b64 v[132:135], v143 offset1:2
	ds_read2_b64 v[26:29], v33 offset0:4 offset1:6
	ds_read2_b64 v[136:139], v143 offset0:4 offset1:6
	s_addk_i32 s5, 0x80
	s_cmpk_eq_i32 s5, 0x200
	s_waitcnt lgkmcnt(3)
	s_waitcnt lgkmcnt(2)
	v_pk_mul_f32 v[30:31], v[4:5], v[22:23] op_sel:[0,1] op_sel_hi:[1,0]
	v_pk_mul_f32 v[140:141], v[114:115], v[132:133] op_sel:[0,1] op_sel_hi:[1,0]
	v_pk_mul_f32 v[4:5], v[4:5], v[22:23]
	v_pk_mul_f32 v[114:115], v[114:115], v[132:133]
	v_add_f32_e32 v30, v30, v31
	v_add_f32_e32 v140, v140, v141
	v_sub_f32_e32 v4, v4, v5
	v_sub_f32_e32 v114, v114, v115
	v_cndmask_b32_e64 v4, -v30, v4, vcc
	v_cndmask_b32_e64 v114, -v140, v114, vcc
	v_cndmask_b32_e32 v5, v9, v8, vcc
	v_cndmask_b32_e32 v115, v119, v118, vcc
	s_nop 1
	s_nop 1
	v_mfma_f32_16x16x4_f32 v[0:3], v4, v5, v[0:3]
	v_mfma_f32_16x16x4_f32 v[110:113], v114, v115, v[110:113]
	v_mul_f32_e64 v4, v6, v25
	v_mul_f32_e64 v114, v116, v135
	v_mul_f32_e64 v5, v7, v24
	v_mul_f32_e64 v115, v117, v134
	v_add_f32_e32 v8, v4, v5
	v_add_f32_e32 v118, v114, v115
	v_mul_f32_e64 v4, v6, v24
	v_mul_f32_e64 v114, v116, v134
	v_mul_f32_e64 v5, v7, v25
	v_mul_f32_e64 v115, v117, v135
	v_sub_f32_e32 v4, v4, v5
	v_sub_f32_e32 v114, v114, v115
	v_cndmask_b32_e64 v4, -v8, v4, vcc
	v_cndmask_b32_e64 v114, -v118, v114, vcc
	v_cndmask_b32_e32 v5, v11, v10, vcc
	v_cndmask_b32_e32 v115, v121, v120, vcc
	s_nop 1
	s_nop 1
	v_mfma_f32_16x16x4_f32 v[0:3], v4, v5, v[0:3]
	v_mfma_f32_16x16x4_f32 v[110:113], v114, v115, v[110:113]
	ds_read2_b64 v[4:7], v32 offset0:64 offset1:96
	ds_read2_b64 v[114:117], v142 offset0:64 offset1:96
	ds_read2_b64 v[8:11], v20 offset0:64 offset1:96
	ds_read2_b64 v[118:121], v130 offset0:64 offset1:96
	s_waitcnt lgkmcnt(3)
	s_waitcnt lgkmcnt(2)
	v_mul_f32_e64 v22, v4, v27
	v_mul_f32_e64 v132, v114, v137
	v_mul_f32_e64 v23, v5, v26
	v_mul_f32_e64 v133, v115, v136
	v_pk_mul_f32 v[4:5], v[4:5], v[26:27]
	v_pk_mul_f32 v[114:115], v[114:115], v[136:137]
	v_add_f32_e32 v22, v22, v23
	v_add_f32_e32 v132, v132, v133
	v_sub_f32_e32 v4, v4, v5
	v_sub_f32_e32 v114, v114, v115
	v_cndmask_b32_e64 v4, -v22, v4, vcc
	v_cndmask_b32_e64 v114, -v132, v114, vcc
	s_waitcnt lgkmcnt(1)
	s_waitcnt lgkmcnt(0)
; __device__ __forceinline__ void ssm_gen(LAS unsigned char* lds, const Args& a, int layer, int g, int j8) {
;     ...
;             for (int st = 0; st < 32; ++st) {
;                 const int p = 2 * st + (kq >> 1);
;                 const f32x2 c = CT[(dir * 64 + p) * 16 + col], w = PW[(dir * 33 + d) * 64 + p], bb = BB[(dir * 64 + p) * 16 + col];
;                 const float av = part ? -(c.x * w.y + c.y * w.x) : (c.x * w.x - c.y * w.y);
;                 const float bv = part ? bb.y : bb.x;
;                 acc = __builtin_amdgcn_mfma_f32_16x16x4f32(av, bv, acc, 0, 0, 0);
;             }
; #pragma unroll
;             for (int i = 0; i < 4; ++i) KC[(dir * 32 + d) * KCS + (4 * kq + i) * 16 + col] = acc[i];
;         }
	v_cndmask_b32_e32 v5, v9, v8, vcc
	v_cndmask_b32_e32 v115, v119, v118, vcc
	s_nop 1
	s_nop 1
	v_mfma_f32_16x16x4_f32 v[0:3], v4, v5, v[0:3]
	v_mfma_f32_16x16x4_f32 v[110:113], v114, v115, v[110:113]
	v_mul_f32_e64 v4, v6, v29
	v_mul_f32_e64 v114, v116, v139
	v_mul_f32_e64 v5, v7, v28
	v_mul_f32_e64 v115, v117, v138
	v_add_f32_e32 v8, v4, v5
	v_add_f32_e32 v118, v114, v115
	v_mul_f32_e64 v4, v6, v28
	v_mul_f32_e64 v114, v116, v138
	v_mul_f32_e64 v5, v7, v29
	v_mul_f32_e64 v115, v117, v139
	v_sub_f32_e32 v4, v4, v5
	v_sub_f32_e32 v114, v114, v115
	v_cndmask_b32_e64 v4, -v8, v4, vcc
	v_cndmask_b32_e64 v114, -v118, v114, vcc
	v_cndmask_b32_e32 v5, v11, v10, vcc
	v_cndmask_b32_e32 v115, v121, v120, vcc
	s_nop 1
	s_nop 1
	v_mfma_f32_16x16x4_f32 v[0:3], v4, v5, v[0:3]
	v_mfma_f32_16x16x4_f32 v[110:113], v114, v115, v[110:113]
	ds_read2_b64 v[4:7], v32 offset0:128 offset1:160
	ds_read2_b64 v[114:117], v142 offset0:128 offset1:160
	ds_read2_b64 v[8:11], v33 offset0:8 offset1:10
	ds_read2_b64 v[118:121], v143 offset0:8 offset1:10
	ds_read2_b64 v[22:25], v20 offset0:128 offset1:160
	ds_read2_b64 v[132:135], v130 offset0:128 offset1:160
	s_waitcnt lgkmcnt(3)
	s_waitcnt lgkmcnt(2)
	v_mul_f32_e64 v26, v4, v9
	v_mul_f32_e64 v136, v114, v119
	v_mul_f32_e64 v27, v5, v8
	v_mul_f32_e64 v137, v115, v118
	v_pk_mul_f32 v[4:5], v[4:5], v[8:9]
	v_pk_mul_f32 v[114:115], v[114:115], v[118:119]
	v_add_f32_e32 v26, v26, v27
	v_add_f32_e32 v136, v136, v137
	v_sub_f32_e32 v4, v4, v5
	v_sub_f32_e32 v114, v114, v115
	v_cndmask_b32_e64 v4, -v26, v4, vcc
	v_cndmask_b32_e64 v114, -v136, v114, vcc
	s_waitcnt lgkmcnt(1)
	s_waitcnt lgkmcnt(0)
	v_cndmask_b32_e32 v5, v23, v22, vcc
	v_cndmask_b32_e32 v115, v133, v132, vcc
	s_nop 1
	s_nop 1
	v_mfma_f32_16x16x4_f32 v[0:3], v4, v5, v[0:3]
	v_mfma_f32_16x16x4_f32 v[110:113], v114, v115, v[110:113]
	v_mul_f32_e64 v4, v6, v11
	v_mul_f32_e64 v114, v116, v121
	v_mul_f32_e64 v5, v7, v10
	v_mul_f32_e64 v115, v117, v120
	v_add_f32_e32 v8, v4, v5
	v_add_f32_e32 v118, v114, v115
	v_mul_f32_e64 v4, v6, v10
	v_mul_f32_e64 v114, v116, v120
	v_mul_f32_e64 v5, v7, v11
	v_mul_f32_e64 v115, v117, v121
	v_sub_f32_e32 v4, v4, v5
	v_sub_f32_e32 v114, v114, v115
	v_cndmask_b32_e64 v4, -v8, v4, vcc
	v_cndmask_b32_e64 v114, -v118, v114, vcc
	v_cndmask_b32_e32 v5, v25, v24, vcc
	v_cndmask_b32_e32 v115, v135, v134, vcc
	s_nop 1
	s_nop 1
	v_mfma_f32_16x16x4_f32 v[8:11], v4, v5, v[0:3]
	v_mfma_f32_16x16x4_f32 v[118:121], v114, v115, v[110:113]
	ds_read2_b64 v[0:3], v32 offset0:192 offset1:224
	ds_read2_b64 v[110:113], v142 offset0:192 offset1:224
	ds_read2_b64 v[4:7], v33 offset0:12 offset1:14
	ds_read2_b64 v[114:117], v143 offset0:12 offset1:14
	ds_read2_b64 v[22:25], v20 offset0:192 offset1:224
	ds_read2_b64 v[132:135], v130 offset0:192 offset1:224
	v_add_u32_e32 v20, 0x800, v20
	v_add_u32_e32 v130, 0x800, v130
	s_waitcnt lgkmcnt(3)
	s_waitcnt lgkmcnt(2)
	v_pk_mul_f32 v[26:27], v[0:1], v[4:5] op_sel:[0,1] op_sel_hi:[1,0]
	v_pk_mul_f32 v[136:137], v[110:111], v[114:115] op_sel:[0,1] op_sel_hi:[1,0]
	v_pk_mul_f32 v[0:1], v[0:1], v[4:5]
	v_pk_mul_f32 v[110:111], v[110:111], v[114:115]
	v_add_f32_e32 v26, v26, v27
	v_add_f32_e32 v136, v136, v137
	v_sub_f32_e32 v0, v0, v1
	v_sub_f32_e32 v110, v110, v111
	v_cndmask_b32_e64 v0, -v26, v0, vcc
	v_cndmask_b32_e64 v110, -v136, v110, vcc
	s_waitcnt lgkmcnt(1)
	s_waitcnt lgkmcnt(0)
	v_cndmask_b32_e32 v1, v23, v22, vcc
	v_cndmask_b32_e32 v111, v133, v132, vcc
	s_nop 1
	s_nop 1
	v_mfma_f32_16x16x4_f32 v[8:11], v0, v1, v[8:11]
	v_mfma_f32_16x16x4_f32 v[118:121], v110, v111, v[118:121]
	v_mul_f32_e64 v0, v2, v7
	v_mul_f32_e64 v110, v112, v117
	v_mul_f32_e64 v1, v3, v6
	v_mul_f32_e64 v111, v113, v116
	v_add_f32_e32 v4, v0, v1
	v_add_f32_e32 v114, v110, v111
	v_mul_f32_e64 v0, v2, v6
	v_mul_f32_e64 v110, v112, v116
	v_mul_f32_e64 v1, v3, v7
	v_mul_f32_e64 v111, v113, v117
	v_sub_f32_e32 v0, v0, v1
	v_sub_f32_e32 v110, v110, v111
	v_cndmask_b32_e64 v0, -v4, v0, vcc
	v_cndmask_b32_e64 v110, -v114, v110, vcc
	v_cndmask_b32_e32 v1, v25, v24, vcc
	v_cndmask_b32_e32 v111, v135, v134, vcc
	s_nop 1
	s_nop 1
	v_mfma_f32_16x16x4_f32 v[0:3], v0, v1, v[8:11]
	v_mfma_f32_16x16x4_f32 v[110:113], v110, v111, v[118:121]
	s_cbranch_scc0 .Lkc_trip
	v_cmp_gt_i32_e64 s[38:39], s82, v13
	v_sub_u32_e32 v4, v13, v19
	s_nop 1
	v_cndmask_b32_e64 v5, 32, 0, s[38:39]
	v_add_u32_e32 v4, v4, v5
	s_movk_i32 s1, 0x410
	v_mad_u64_u32 v[4:5], s[8:9], v4, s1, v[14:15]
	s_nop 3
	ds_write2_b32 v4, v0, v1 offset1:16
	ds_write2_b32 v4, v2, v3 offset0:32 offset1:48
	v_cmp_gt_i32_e64 s[38:39], s82, v144
	v_sub_u32_e32 v114, v144, v129
	s_nop 1
	v_cndmask_b32_e64 v115, 32, 0, s[38:39]
	v_add_u32_e32 v114, v114, v115
	s_movk_i32 s1, 0x410
	v_mad_u64_u32 v[114:115], s[8:9], v114, s1, v[14:15]
	s_nop 3
	ds_write2_b32 v114, v110, v111 offset1:16
	ds_write2_b32 v114, v112, v113 offset0:32 offset1:48
	v_add_u32_e32 v13, 16, v13
	s_add_u32 s7, s7, 1
	s_cmp_lt_u32 s7, 2
	s_cbranch_scc1 .Lkc_pair
	v_cmp_gt_i32_e64 s[38:39], 36, v13
	s_nop 1
	s_and_b64 exec, exec, s[38:39]
	s_cbranch_execz .LBB0_371
